# adds: final norm loop requests both halves of a row together and no longer drains at the loop top
# speedup vs baseline: 1.0115x; 1.0043x over previous
.LBB0_1760:
	s_cmp_lt_i32 s92, 13
	s_cselect_b64 s[0:1], -1, 0
	s_cmp_gt_i32 s93, 12
	s_cselect_b64 s[2:3], -1, 0
	s_and_b64 s[0:1], s[0:1], s[2:3]
	s_andn2_b64 vcc, exec, s[0:1]
	s_cbranch_vccnz .LBB0_1764
	s_lshl_b32 s0, s90, 3
	s_add_i32 s0, s0, s33
	s_cmpk_gt_i32 s0, 0x41ff
	s_cbranch_scc1 .LBB0_1764
	v_readlane_b32 s4, v254, 25
	v_lshlrev_b32_e32 v16, 5, v174
	v_readlane_b32 s18, v254, 39
	v_readlane_b32 s19, v254, 40
	s_waitcnt lgkmcnt(0)
	s_nop 3
	global_load_dwordx4 v[0:3], v16, s[18:19] offset:16
	global_load_dwordx4 v[4:7], v16, s[18:19]
	global_load_dwordx4 v[8:11], v16, s[18:19] offset:2064
	global_load_dwordx4 v[12:15], v16, s[18:19] offset:2048
	v_readlane_b32 s5, v254, 26
	s_lshl_b32 s2, s88, 3
	s_ashr_i32 s1, s0, 31
	v_readlane_b32 s6, v254, 27
	v_readlane_b32 s7, v254, 28
	v_readlane_b32 s8, v254, 29
	v_readlane_b32 s9, v254, 30
	v_readlane_b32 s10, v254, 31
	v_readlane_b32 s11, v254, 32
	s_lshl_b64 s[4:5], s[0:1], 11
	s_ashr_i32 s3, s2, 31
	v_lshl_or_b32 v18, v174, 4, s4
	v_mov_b32_e32 v19, s5
	s_lshl_b64 s[4:5], s[2:3], 11
	s_lshl_b64 s[6:7], s[0:1], 6
	s_lshl_b64 s[8:9], s[2:3], 6
	s_lshl_b64 s[10:11], s[0:1], 12
	s_add_u32 s10, s84, s10
	v_mov_b32_e32 v17, 0
	s_addc_u32 s11, s85, s11
	v_lshl_add_u64 v[20:21], s[10:11], 0, v[16:17]
	s_mov_b64 s[10:11], 0x810
	v_readlane_b32 s14, v254, 35
	v_readlane_b32 s15, v254, 36
	v_lshl_add_u64 v[20:21], v[20:21], 0, s[10:11]
	s_lshl_b64 s[10:11], s[2:3], 12
	v_mov_b32_e32 v16, 0xb00000
	v_mov_b32_e32 v22, 0x358637bd
	s_mov_b32 s1, 0x13800000
	v_readlane_b32 s12, v254, 33
	v_readlane_b32 s13, v254, 34
	v_readlane_b32 s16, v254, 37
	v_readlane_b32 s17, v254, 38
	s_mov_b64 s[14:15], s[18:19]
	s_waitcnt vmcnt(0)
.LBB0_1763:
	s_add_u32 s12, s86, s6
	v_lshl_add_u64 v[24:25], s[86:87], 0, v[18:19]
	s_addc_u32 s13, s87, s7
	v_add_co_u32_e32 v44, vcc, s1, v24
	s_add_u32 s14, s12, 0xb00000
	s_nop 0
	v_addc_co_u32_e32 v45, vcc, 0, v25, vcc
	global_load_dwordx4 v[24:27], v16, s[12:13]
	s_addc_u32 s15, s13, 0
	global_load_dwordx4 v[28:31], v17, s[14:15] offset:48
	global_load_dwordx4 v[32:35], v17, s[14:15] offset:32
	global_load_dwordx4 v[36:39], v17, s[14:15] offset:16
	global_load_dwordx4 v[40:43], v[44:45], off nt
	global_load_dwordx4 v[50:53], v[44:45], off offset:1024 nt
	s_add_i32 s0, s0, s2
	s_add_u32 s6, s6, s8
	s_addc_u32 s7, s7, s9
	v_lshl_add_u64 v[18:19], v[18:19], 0, s[4:5]
	s_cmpk_lt_i32 s0, 0x4200
	s_waitcnt vmcnt(5)
	v_mov_b32_e32 v46, v25
	v_mov_b32_e32 v47, v26
	v_mov_b32_e32 v25, v27
	v_pk_add_f32 v[24:25], v[46:47], v[24:25]
	s_waitcnt vmcnt(3)
	v_add_f32_e32 v32, v32, v33
	v_add_f32_e32 v23, v24, v25
	s_waitcnt vmcnt(2)
	v_mov_b32_e32 v24, v37
	v_mov_b32_e32 v25, v38
	v_mov_b32_e32 v37, v39
	v_pk_add_f32 v[24:25], v[24:25], v[36:37]
	v_add_f32_e32 v34, v34, v35
	v_pk_add_f32 v[24:25], v[24:25], v[24:25] op_sel:[0,1] op_sel_hi:[1,0]
	v_mov_b32_e32 v39, v28
	v_mov_b32_e32 v33, v30
	v_mov_b32_e32 v35, v31
	v_add_f32_e32 v38, 0, v23
	v_mov_b32_e32 v25, v29
	v_pk_add_f32 v[30:31], v[32:33], v[34:35]
	v_pk_add_f32 v[24:25], v[38:39], v[24:25]
	s_waitcnt vmcnt(1)
	v_lshlrev_b32_e32 v26, 16, v40
	v_pk_add_f32 v[24:25], v[24:25], v[30:31]
	v_and_b32_e32 v27, 0xffff0000, v40
	v_add_f32_e32 v23, v24, v25
	v_fmamk_f32 v23, v23, 0x3a800000, v22
	v_rsq_f32_e32 v32, v23
	v_lshlrev_b32_e32 v40, 16, v41
	v_and_b32_e32 v41, 0xffff0000, v41
	v_lshlrev_b32_e32 v48, 16, v42
	v_and_b32_e32 v49, 0xffff0000, v42
	v_lshlrev_b32_e32 v42, 16, v43
	v_and_b32_e32 v43, 0xffff0000, v43
	v_pk_mul_f32 v[24:25], v[32:33], v[26:27] op_sel_hi:[0,1]
	v_pk_mul_f32 v[26:27], v[32:33], v[40:41] op_sel_hi:[0,1]
	v_pk_mul_f32 v[28:29], v[32:33], v[48:49] op_sel_hi:[0,1]
	v_pk_mul_f32 v[30:31], v[32:33], v[42:43] op_sel_hi:[0,1]
	v_pk_mul_f32 v[26:27], v[6:7], v[26:27]
	v_pk_mul_f32 v[24:25], v[4:5], v[24:25]
	v_pk_mul_f32 v[30:31], v[2:3], v[30:31]
	v_pk_mul_f32 v[28:29], v[0:1], v[28:29]
	global_store_dwordx4 v[20:21], v[24:27], off offset:-2064 nt
	global_store_dwordx4 v[20:21], v[28:31], off offset:-2048 nt
	s_waitcnt vmcnt(2)
	s_nop 1
	v_lshlrev_b32_e32 v28, 16, v50
	v_and_b32_e32 v29, 0xffff0000, v50
	v_lshlrev_b32_e32 v24, 16, v51
	v_and_b32_e32 v25, 0xffff0000, v51
	v_lshlrev_b32_e32 v30, 16, v52
	v_and_b32_e32 v31, 0xffff0000, v52
	v_lshlrev_b32_e32 v26, 16, v53
	v_and_b32_e32 v27, 0xffff0000, v53
	v_pk_mul_f32 v[28:29], v[32:33], v[28:29] op_sel_hi:[0,1]
	v_pk_mul_f32 v[24:25], v[32:33], v[24:25] op_sel_hi:[0,1]
	v_pk_mul_f32 v[34:35], v[32:33], v[30:31] op_sel_hi:[0,1]
	v_pk_mul_f32 v[30:31], v[32:33], v[26:27] op_sel_hi:[0,1]
	v_pk_mul_f32 v[26:27], v[14:15], v[24:25]
	v_pk_mul_f32 v[24:25], v[12:13], v[28:29]
	v_pk_mul_f32 v[30:31], v[10:11], v[30:31]
	v_pk_mul_f32 v[28:29], v[8:9], v[34:35]
	global_store_dwordx4 v[20:21], v[24:27], off offset:-16 nt
	global_store_dwordx4 v[20:21], v[28:31], off nt
	v_lshl_add_u64 v[20:21], v[20:21], 0, s[10:11]
	s_cbranch_scc1 .LBB0_1763
